# attention output epilogue: f32->bf16 by v_cvt_pk_bf16_f32 instead of the bfe/add3 rounding pair
# speedup vs baseline: 1.0013x; 1.0013x over previous
; __device__ __forceinline__ unsigned f2bf(float f) { unsigned u = __builtin_bit_cast(unsigned, f); return (u + 0x7fffu + ((u >> 16) & 1u)) >> 16; }
; __device__ __forceinline__ int crow(int r, int hi) { return (r & 3) + 8 * (r >> 2) + 4 * hi; }
; __device__ __forceinline__ void attn_unit(const bf16* __restrict__ Qb, const bf16* __restrict__ Kh, const bf16* __restrict__ Vh, bf16* __restrict__ Ob, int seq, char* lds) {
;     ...
;     if (hi == 0) wsf[r32] = l_reg; asm volatile("s_waitcnt lgkmcnt(0)" ::: "memory");
;     float rli[16];
; #pragma unroll
;     for (int r = 0; r < 16; ++r) rli[r] = __builtin_amdgcn_rcpf(wsf[crow(r, hi)]);
;     bf16* Ow = Ob + (long)(wid * QBLK) * 128;
;     {
;         char* stg = lds + 53248 + wid * 8192;
; #pragma unroll
;         for (int r = 0; r < 16; ++r) { const int orow = crow(r, hi);
; #pragma unroll
;             for (int d0 = 0; d0 < 4; ++d0) *(unsigned short*)(stg + (orow * 128 + d0 * 32 + r32) * 2) = (unsigned short)f2bf(o[d0][r] * rli[r]); }
.LBB0_529:
	s_or_b64 exec, exec, s[10:11]
	s_waitcnt lgkmcnt(0)
	v_add_u32_e32 v74, v143, v144
	ds_read_b128 v[66:69], v74 offset:49152
	ds_read_b128 v[70:73], v74 offset:49184
	v_lshl_add_u32 v84, v155, 13, 0
	s_lshl_b64 s[6:7], s[6:7], 8
	s_add_u32 s6, s44, s6
	s_waitcnt lgkmcnt(1)
	v_rcp_f32_e32 v75, v66
	v_rcp_f32_e32 v76, v67
	v_rcp_f32_e32 v77, v68
	v_rcp_f32_e32 v78, v69
	v_mul_f32_e32 v2, v2, v75
	v_cvt_pk_bf16_f32 v2, v2, v2
	v_lshlrev_b32_e32 v85, 1, v153
	v_lshl_or_b32 v85, v154, 10, v85
	v_add_u32_e32 v85, v84, v85
	ds_write_b16_d16_hi v85, v2 offset:53248
	v_mul_f32_e32 v2, v18, v75
	v_cvt_pk_bf16_f32 v2, v2, v2
	ds_write_b16_d16_hi v85, v2 offset:53312
	v_mul_f32_e32 v2, v34, v75
	v_cvt_pk_bf16_f32 v2, v2, v2
	ds_write_b16_d16_hi v85, v2 offset:53376
	v_mul_f32_e32 v2, v50, v75
	v_cvt_pk_bf16_f32 v2, v2, v2
	ds_write_b16_d16_hi v85, v2 offset:53440
	v_mul_f32_e32 v2, v3, v76
	v_cvt_pk_bf16_f32 v2, v2, v2
	ds_write_b16_d16_hi v85, v2 offset:53504
	v_mul_f32_e32 v2, v19, v76
	v_cvt_pk_bf16_f32 v2, v2, v2
	ds_write_b16_d16_hi v85, v2 offset:53568
	v_mul_f32_e32 v2, v35, v76
	v_cvt_pk_bf16_f32 v2, v2, v2
	ds_write_b16_d16_hi v85, v2 offset:53632
	v_mul_f32_e32 v2, v51, v76
	v_cvt_pk_bf16_f32 v2, v2, v2
	ds_write_b16_d16_hi v85, v2 offset:53696
	v_mul_f32_e32 v2, v4, v77
	v_cvt_pk_bf16_f32 v2, v2, v2
	ds_write_b16_d16_hi v85, v2 offset:53760
	v_mul_f32_e32 v2, v20, v77
	v_cvt_pk_bf16_f32 v2, v2, v2
	ds_write_b16_d16_hi v85, v2 offset:53824
	v_mul_f32_e32 v2, v36, v77
	v_cvt_pk_bf16_f32 v2, v2, v2
	ds_write_b16_d16_hi v85, v2 offset:53888
	v_mul_f32_e32 v2, v52, v77
	v_cvt_pk_bf16_f32 v2, v2, v2
	ds_write_b16_d16_hi v85, v2 offset:53952
	v_mul_f32_e32 v2, v5, v78
	v_cvt_pk_bf16_f32 v2, v2, v2
	ds_write_b16_d16_hi v85, v2 offset:54016
	v_mul_f32_e32 v2, v21, v78
	v_cvt_pk_bf16_f32 v2, v2, v2
	ds_write_b16_d16_hi v85, v2 offset:54080
	v_mul_f32_e32 v2, v37, v78
	v_bfe_u32 v3, v2, 16, 1
	s_waitcnt lgkmcnt(14)
	v_rcp_f32_e32 v79, v70
	v_add3_u32 v2, v2, v3, s48
	ds_write_b16_d16_hi v85, v2 offset:54144
	v_mul_f32_e32 v2, v53, v78
	v_cvt_pk_bf16_f32 v2, v2, v2
	ds_write_b16_d16_hi v85, v2 offset:54208
	v_mul_f32_e32 v2, v6, v79
	v_cvt_pk_bf16_f32 v2, v2, v2
	ds_write_b16_d16_hi v85, v2 offset:55296
	v_mul_f32_e32 v2, v22, v79
	v_cvt_pk_bf16_f32 v2, v2, v2
	ds_write_b16_d16_hi v85, v2 offset:55360
	v_mul_f32_e32 v2, v38, v79
	v_bfe_u32 v3, v2, 16, 1
	v_rcp_f32_e32 v80, v71
	v_add3_u32 v2, v2, v3, s48
	ds_write_b16_d16_hi v85, v2 offset:55424
	v_mul_f32_e32 v2, v54, v79
	v_cvt_pk_bf16_f32 v2, v2, v2
	ds_write_b16_d16_hi v85, v2 offset:55488
	v_mul_f32_e32 v2, v7, v80
	v_cvt_pk_bf16_f32 v2, v2, v2
	ds_write_b16_d16_hi v85, v2 offset:55552
	v_mul_f32_e32 v2, v23, v80
	v_cvt_pk_bf16_f32 v2, v2, v2
	ds_write_b16_d16_hi v85, v2 offset:55616
	v_mul_f32_e32 v2, v39, v80
	v_bfe_u32 v3, v2, 16, 1
	v_rcp_f32_e32 v81, v72
	v_add3_u32 v2, v2, v3, s48
	ds_write_b16_d16_hi v85, v2 offset:55680
	v_mul_f32_e32 v2, v55, v80
	v_cvt_pk_bf16_f32 v2, v2, v2
	ds_write_b16_d16_hi v85, v2 offset:55744
	v_mul_f32_e32 v2, v8, v81
	v_cvt_pk_bf16_f32 v2, v2, v2
	ds_write_b16_d16_hi v85, v2 offset:55808
	v_mul_f32_e32 v2, v24, v81
	v_cvt_pk_bf16_f32 v2, v2, v2
	ds_write_b16_d16_hi v85, v2 offset:55872
	v_mul_f32_e32 v2, v40, v81
	v_bfe_u32 v3, v2, 16, 1
	v_rcp_f32_e32 v82, v73
	v_add3_u32 v2, v2, v3, s48
	ds_write_b16_d16_hi v85, v2 offset:55936
	v_mul_f32_e32 v2, v56, v81
	v_cvt_pk_bf16_f32 v2, v2, v2
	ds_write_b16_d16_hi v85, v2 offset:56000
	v_mul_f32_e32 v2, v9, v82
	v_cvt_pk_bf16_f32 v2, v2, v2
	ds_read_b128 v[66:69], v74 offset:49216
	ds_read_b128 v[70:73], v74 offset:49248
	ds_write_b16_d16_hi v85, v2 offset:56064
	v_mul_f32_e32 v2, v25, v82
	v_cvt_pk_bf16_f32 v2, v2, v2
	ds_write_b16_d16_hi v85, v2 offset:56128
	v_mul_f32_e32 v2, v41, v82
	v_bfe_u32 v3, v2, 16, 1
	s_waitcnt lgkmcnt(3)
	v_rcp_f32_e32 v74, v66
	v_add3_u32 v2, v2, v3, s48
	ds_write_b16_d16_hi v85, v2 offset:56192
	v_mul_f32_e32 v2, v57, v82
	v_cvt_pk_bf16_f32 v2, v2, v2
	ds_write_b16_d16_hi v85, v2 offset:56256
	v_mul_f32_e32 v2, v10, v74
	v_cvt_pk_bf16_f32 v2, v2, v2
	ds_write_b16_d16_hi v85, v2 offset:57344
	v_mul_f32_e32 v2, v26, v74
	v_cvt_pk_bf16_f32 v2, v2, v2
	ds_write_b16_d16_hi v85, v2 offset:57408
	v_mul_f32_e32 v2, v42, v74
	v_bfe_u32 v3, v2, 16, 1
	v_rcp_f32_e32 v83, v67
	v_add3_u32 v2, v2, v3, s48
	ds_write_b16_d16_hi v85, v2 offset:57472
	v_mul_f32_e32 v2, v58, v74
	v_cvt_pk_bf16_f32 v2, v2, v2
	ds_write_b16_d16_hi v85, v2 offset:57536
	v_mul_f32_e32 v2, v11, v83
	v_cvt_pk_bf16_f32 v2, v2, v2
	ds_write_b16_d16_hi v85, v2 offset:57600
	v_mul_f32_e32 v2, v27, v83
	v_cvt_pk_bf16_f32 v2, v2, v2
	ds_write_b16_d16_hi v85, v2 offset:57664
	v_mul_f32_e32 v2, v43, v83
	v_bfe_u32 v3, v2, 16, 1
	v_rcp_f32_e32 v68, v68
	v_add3_u32 v2, v2, v3, s48
	ds_write_b16_d16_hi v85, v2 offset:57728
	v_mul_f32_e32 v2, v59, v83
	v_cvt_pk_bf16_f32 v2, v2, v2
	ds_write_b16_d16_hi v85, v2 offset:57792
	v_mul_f32_e32 v2, v12, v68
	v_cvt_pk_bf16_f32 v2, v2, v2
	ds_write_b16_d16_hi v85, v2 offset:57856
	v_mul_f32_e32 v2, v28, v68
	v_cvt_pk_bf16_f32 v2, v2, v2
	ds_write_b16_d16_hi v85, v2 offset:57920
	v_mul_f32_e32 v2, v44, v68
	v_bfe_u32 v3, v2, 16, 1
	v_rcp_f32_e32 v69, v69
	v_add3_u32 v2, v2, v3, s48
	ds_write_b16_d16_hi v85, v2 offset:57984
	v_mul_f32_e32 v2, v60, v68
	v_cvt_pk_bf16_f32 v2, v2, v2
	ds_write_b16_d16_hi v85, v2 offset:58048
	v_mul_f32_e32 v2, v13, v69
	v_cvt_pk_bf16_f32 v2, v2, v2
	ds_write_b16_d16_hi v85, v2 offset:58112
	v_mul_f32_e32 v2, v29, v69
	v_cvt_pk_bf16_f32 v2, v2, v2
	ds_write_b16_d16_hi v85, v2 offset:58176
	v_mul_f32_e32 v2, v45, v69
	v_bfe_u32 v3, v2, 16, 1
	s_waitcnt lgkmcnt(14)
; __device__ __forceinline__ unsigned f2bf(float f) { unsigned u = __builtin_bit_cast(unsigned, f); return (u + 0x7fffu + ((u >> 16) & 1u)) >> 16; }
; __device__ __forceinline__ int crow(int r, int hi) { return (r & 3) + 8 * (r >> 2) + 4 * hi; }
; __device__ __forceinline__ void attn_unit(const bf16* __restrict__ Qb, const bf16* __restrict__ Kh, const bf16* __restrict__ Vh, bf16* __restrict__ Ob, int seq, char* lds) {
;     ...
;         for (int r = 0; r < 16; ++r) { const int orow = crow(r, hi);
; #pragma unroll
;             for (int d0 = 0; d0 < 4; ++d0) *(unsigned short*)(stg + (orow * 128 + d0 * 32 + r32) * 2) = (unsigned short)f2bf(o[d0][r] * rli[r]); }
;         asm volatile("s_waitcnt lgkmcnt(0)" ::: "memory");
; #pragma unroll
;         for (int i = 0; i < 8; ++i) { const int row = i * 4 + (lane >> 4), ch = lane & 15; const v4u v = *(const v4u*)(stg + row * 256 + ch * 16); *(v4u*)(Ow + (long)row * 128 + ch * 8) = v; }
;     }
;     __syncthreads();
	v_rcp_f32_e32 v70, v70
	v_add3_u32 v2, v2, v3, s48
	ds_write_b16_d16_hi v85, v2 offset:58240
	v_mul_f32_e32 v2, v61, v69
	v_cvt_pk_bf16_f32 v2, v2, v2
	ds_write_b16_d16_hi v85, v2 offset:58304
	v_mul_f32_e32 v2, v14, v70
	v_cvt_pk_bf16_f32 v2, v2, v2
	ds_write_b16_d16_hi v85, v2 offset:59392
	v_mul_f32_e32 v2, v30, v70
	v_cvt_pk_bf16_f32 v2, v2, v2
	ds_write_b16_d16_hi v85, v2 offset:59456
	v_mul_f32_e32 v2, v46, v70
	v_bfe_u32 v3, v2, 16, 1
	v_rcp_f32_e32 v71, v71
	v_add3_u32 v2, v2, v3, s48
	ds_write_b16_d16_hi v85, v2 offset:59520
	v_mul_f32_e32 v2, v62, v70
	v_cvt_pk_bf16_f32 v2, v2, v2
	ds_write_b16_d16_hi v85, v2 offset:59584
	v_mul_f32_e32 v2, v15, v71
	v_cvt_pk_bf16_f32 v2, v2, v2
	ds_write_b16_d16_hi v85, v2 offset:59648
	v_mul_f32_e32 v2, v31, v71
	v_cvt_pk_bf16_f32 v2, v2, v2
	ds_write_b16_d16_hi v85, v2 offset:59712
	v_mul_f32_e32 v2, v47, v71
	v_bfe_u32 v3, v2, 16, 1
	v_rcp_f32_e32 v72, v72
	v_add3_u32 v2, v2, v3, s48
	ds_write_b16_d16_hi v85, v2 offset:59776
	v_mul_f32_e32 v2, v63, v71
	v_cvt_pk_bf16_f32 v2, v2, v2
	ds_write_b16_d16_hi v85, v2 offset:59840
	v_mul_f32_e32 v2, v16, v72
	v_cvt_pk_bf16_f32 v2, v2, v2
	ds_write_b16_d16_hi v85, v2 offset:59904
	v_mul_f32_e32 v2, v32, v72
	v_cvt_pk_bf16_f32 v2, v2, v2
	ds_write_b16_d16_hi v85, v2 offset:59968
	v_mul_f32_e32 v2, v48, v72
	v_bfe_u32 v3, v2, 16, 1
	v_rcp_f32_e32 v73, v73
	v_add3_u32 v2, v2, v3, s48
	ds_write_b16_d16_hi v85, v2 offset:60032
	v_mul_f32_e32 v2, v64, v72
	v_cvt_pk_bf16_f32 v2, v2, v2
	ds_write_b16_d16_hi v85, v2 offset:60096
	v_mul_f32_e32 v2, v17, v73
	v_cvt_pk_bf16_f32 v2, v2, v2
	ds_write_b16_d16_hi v85, v2 offset:60160
	v_mul_f32_e32 v2, v33, v73
	v_cvt_pk_bf16_f32 v2, v2, v2
	ds_write_b16_d16_hi v85, v2 offset:60224
	v_mul_f32_e32 v2, v49, v73
	v_cvt_pk_bf16_f32 v2, v2, v2
	ds_write_b16_d16_hi v85, v2 offset:60288
	v_mul_f32_e32 v2, v65, v73
	v_ashrrev_i32_e32 v143, 31, v142
	v_bfe_u32 v3, v2, 16, 1
	s_addc_u32 s7, s45, s7
	v_lshlrev_b64 v[66:67], 8, v[142:143]
	v_add3_u32 v2, v2, v3, s48
	ds_write_b16_d16_hi v85, v2 offset:60352
	v_lshl_add_u64 v[2:3], s[6:7], 0, v[66:67]
	v_and_b32_e32 v4, 0xf0, v140
	v_mov_b32_e32 v5, v138
	v_lshl_add_u64 v[10:11], v[2:3], 0, v[4:5]
	v_lshlrev_b32_e32 v2, 4, v145
	v_add_u32_e32 v18, v84, v4
	v_and_b32_e32 v12, 0x300, v2
	s_waitcnt lgkmcnt(0)
	v_add_u32_e32 v2, v18, v12
	v_or_b32_e32 v14, 0x400, v12
	ds_read_b128 v[2:5], v2 offset:53248
	v_add_u32_e32 v6, v18, v14
	ds_read_b128 v[6:9], v6 offset:53248
	v_mov_b32_e32 v13, v138
	v_lshl_add_u64 v[16:17], v[10:11], 0, v[12:13]
	v_mov_b32_e32 v15, v138
	s_waitcnt lgkmcnt(1)
	global_store_dwordx4 v[16:17], v[2:5], off
	v_or_b32_e32 v16, 0xc00, v12
	v_mov_b32_e32 v17, v138
	v_lshl_add_u64 v[2:3], v[10:11], 0, v[14:15]
	v_or_b32_e32 v14, 0x800, v12
	s_waitcnt lgkmcnt(0)
	global_store_dwordx4 v[2:3], v[6:9], off
	v_add_u32_e32 v2, v18, v14
	ds_read_b128 v[2:5], v2 offset:53248
	v_add_u32_e32 v6, v18, v16
	ds_read_b128 v[6:9], v6 offset:53248
	v_lshl_add_u64 v[14:15], v[10:11], 0, v[14:15]
	s_add_i32 s50, s50, s18
	s_waitcnt lgkmcnt(1)
	global_store_dwordx4 v[14:15], v[2:5], off
	v_or_b32_e32 v14, 0x1000, v12
	v_mov_b32_e32 v15, v138
	v_lshl_add_u64 v[2:3], v[10:11], 0, v[16:17]
	s_waitcnt lgkmcnt(0)
	global_store_dwordx4 v[2:3], v[6:9], off
	v_add_u32_e32 v2, v18, v14
	v_or_b32_e32 v16, 0x1400, v12
	ds_read_b128 v[2:5], v2 offset:53248
	v_add_u32_e32 v6, v18, v16
	ds_read_b128 v[6:9], v6 offset:53248
	v_lshl_add_u64 v[14:15], v[10:11], 0, v[14:15]
	s_add_i32 s49, s49, s18
	s_waitcnt lgkmcnt(1)
	global_store_dwordx4 v[14:15], v[2:5], off
	v_or_b32_e32 v14, 0x1800, v12
	v_or_b32_e32 v12, 0x1c00, v12
	v_lshl_add_u64 v[2:3], v[10:11], 0, v[16:17]
	s_waitcnt lgkmcnt(0)
	global_store_dwordx4 v[2:3], v[6:9], off
	v_add_u32_e32 v2, v18, v14
	ds_read_b128 v[2:5], v2 offset:53248
	v_add_u32_e32 v6, v18, v12
	ds_read_b128 v[6:9], v6 offset:53248
	v_mov_b32_e32 v15, v138
	v_lshl_add_u64 v[14:15], v[10:11], 0, v[14:15]
	s_waitcnt lgkmcnt(1)
	global_store_dwordx4 v[14:15], v[2:5], off
	s_cmpk_gt_i32 s50, 0x1ff
	s_nop 0
	v_lshl_add_u64 v[2:3], v[10:11], 0, v[12:13]
	s_waitcnt lgkmcnt(0)
	global_store_dwordx4 v[2:3], v[6:9], off
	s_barrier
	s_cbranch_scc1 .LBB0_534
